# MLA loops: fewer issue slots per step (stream advance in lane-offset VGPRs, uniform counted vmcnt, LDS lookahead 7 with one lgkmcnt wait per 3 MFMAs)
# baseline (speedup 1.0000x reference)
; template <bool SWA> ...
;     ...
;     const int koff = pkey * ldk + 8 * wv, voff = lane * T + 8 * wv, roff = pkey * 512 + 8 * (wv & 3);
;     const bool do_r = (!SWA) && wv < 4;
;     const int kfo = hi * 1024 + l32 * 16, vfo = AT_KB + hi * 1024 + l32 * 16;
;     ...
;     AT_GLOAD(0, 0); AT_GLOAD(1, AT_BUF);
;     asm volatile("s_waitcnt vmcnt(0)" ::: "memory");
;     __syncthreads();
;     f32x16 o0, o1, negm;
;     float mref = SWA ? m_init : 0.f, lrun = l_init;
; #pragma unroll
;     for (int r = 0; r < 16; ++r) { o0[r] = 0.f; o1[r] = 0.f; negm[r] = -mref; }
.LBB0_1008:
	s_lshr_b32 s6, s12, 5
	s_and_b32 s6, s6, 7
	s_lshl_b32 s15, s6, 7
	s_lshl_b32 s19, s6, 22
	s_lshl_b64 s[6:7], s[4:5], 23
	v_add_u32_e32 v6, s18, v236
	s_lshl_b32 s13, s13, 6
	v_lshl_or_b32 v206, v6, 1, s6
	s_or_b32 s6, s6, s15
	s_lshl_b64 s[4:5], s[4:5], 14
	s_add_u32 s4, s19, s4
	v_mov_b32_e32 v6, s6
	v_mov_b32_e32 v7, s7
	s_addc_u32 s5, 0, s5
	v_mov_b32_e32 v16, v1
	v_mov_b32_e32 v17, v1
	v_lshl_add_u64 v[208:209], v[4:5], 1, v[6:7]
	v_lshl_add_u64 v[210:211], v[2:3], 1, s[4:5]
	v_mov_b32_e32 v2, v1
	v_mov_b32_e32 v3, v1
	v_mov_b32_e32 v4, v1
	v_mov_b32_e32 v5, v1
	v_mov_b32_e32 v6, v1
	v_mov_b32_e32 v7, v1
	v_mov_b32_e32 v8, v1
	v_mov_b32_e32 v9, v1
	v_mov_b32_e32 v10, v1
	v_mov_b32_e32 v11, v1
	v_mov_b32_e32 v12, v1
	v_mov_b32_e32 v13, v1
	v_mov_b32_e32 v14, v1
	v_mov_b32_e32 v15, v1
	v_bfrev_b32_e32 v82, 1
	v_mov_b64_e32 v[32:33], v[16:17]
	v_readlane_b32 s36, v254, 54
	v_mov_b32_e32 v207, s7
	s_mov_b32 s4, 0
	s_mov_b32 s18, 0xa000
	s_movk_i32 s15, 0x5000
	v_mov_b32_e32 v239, 0
	s_mov_b32 s19, -2
	v_mov_b64_e32 v[30:31], v[14:15]
	v_mov_b64_e32 v[28:29], v[12:13]
	v_mov_b64_e32 v[26:27], v[10:11]
	v_mov_b64_e32 v[24:25], v[8:9]
	v_mov_b64_e32 v[22:23], v[6:7]
	v_mov_b64_e32 v[20:21], v[4:5]
	v_mov_b64_e32 v[18:19], v[2:3]
	v_mov_b32_e32 v170, 0
	v_mov_b32_e32 v83, v82
	v_mov_b32_e32 v84, v82
	v_mov_b32_e32 v85, v82
	v_mov_b32_e32 v86, v82
	v_mov_b32_e32 v87, v82
	v_mov_b32_e32 v88, v82
	v_mov_b32_e32 v89, v82
	v_mov_b32_e32 v90, v82
	v_mov_b32_e32 v91, v82
	v_mov_b32_e32 v92, v82
	v_mov_b32_e32 v93, v82
	v_mov_b32_e32 v94, v82
	v_mov_b32_e32 v95, v82
	v_mov_b32_e32 v96, v82
	v_mov_b32_e32 v97, v82
	v_readlane_b32 s38, v254, 56
	v_readlane_b32 s39, v254, 57
	v_readlane_b32 s37, v254, 55
	s_mov_b32 s20, 0xf000
	v_readfirstlane_b32 s6, v208
	v_readfirstlane_b32 s7, v209
	v_readfirstlane_b32 s24, v210
	v_readfirstlane_b32 s25, v211
	s_add_u32 s34, s38, s6
	s_addc_u32 s35, s39, s7
	s_add_u32 s34, s34, 0x17020000
	s_addc_u32 s35, s35, 0
	v_subrev_u32_e32 v154, s6, v208
	s_add_u32 s28, s38, s24
	s_addc_u32 s29, s39, s25
	s_add_u32 s28, s28, 0x18008100
	s_addc_u32 s29, s29, 0
	v_subrev_u32_e32 v156, s24, v210
	v_readfirstlane_b32 s6, v206
	v_readfirstlane_b32 s7, v207
	s_nop 1
	s_add_u32 s38, s38, s6
	s_addc_u32 s39, s39, s7
	s_add_u32 s38, s38, 0x8820300
	s_addc_u32 s39, s39, 0
	v_subrev_u32_e32 v158, s6, v206
	s_add_i32 s24, s14, s18
	s_mov_b32 m0, s24
	s_andn2_b64 vcc, exec, s[16:17]
	global_load_lds_dwordx4 v154, s[34:35]
	s_add_i32 m0, s24, 0x3000
	v_add_u32_e32 v154, 0x10000, v154
	global_load_lds_dwordx4 v156, s[28:29]
	v_add_u32_e32 v156, 0x80, v156
	s_cbranch_vccnz .LmlaLP_nokr
	s_add_i32 m0, s24, 0x2000
	s_nop 0
	global_load_lds_dwordx4 v158, s[38:39]
	v_add_u32_e32 v158, 0x10000, v158

.LmlaL_top:
	v_add_u32_e32 v164, s15, v238
	v_add_u32_e32 v165, s4, v238
	ds_read_b128 v[172:175], v164
	ds_read_b128 v[176:179], v164 offset:512
	ds_read_b128 v[180:183], v164 offset:2048
	ds_read_b128 v[184:187], v164 offset:2560
	ds_read_b128 v[188:191], v164 offset:4096
	ds_read_b128 v[192:195], v164 offset:4608
	ds_read_b128 v[240:243], v164 offset:6144
	s_add_i32 s24, s14, s20
	s_mov_b32 m0, s24
	s_andn2_b64 vcc, exec, s[16:17]
	global_load_lds_dwordx4 v154, s[34:35]
	s_add_i32 m0, s24, 0x3000
	v_add_u32_e32 v154, 0x10000, v154
	global_load_lds_dwordx4 v156, s[28:29]
	v_add_u32_e32 v156, 0x80, v156
	s_cbranch_vccnz .LmlaLA_nokr
	s_add_i32 m0, s24, 0x2000
	s_nop 0
	global_load_lds_dwordx4 v158, s[38:39]
	v_add_u32_e32 v158, 0x10000, v158

.LmlaLA_common:
	s_waitcnt lgkmcnt(4)
	v_mfma_f32_32x32x16_bf16 v[98:113], v[172:175], v[150:153], v[82:97]
	ds_read_b128 v[244:247], v164 offset:6656
	v_exp_f32_e32 v66, v66
	v_exp_f32_e32 v67, v67
	v_exp_f32_e32 v68, v68
	v_mfma_f32_32x32x16_bf16 v[114:129], v[176:179], v[150:153], v[82:97]
	ds_read_b128 v[248:251], v164 offset:8192
	v_exp_f32_e32 v69, v69
	v_exp_f32_e32 v70, v70
	v_exp_f32_e32 v71, v71
	v_mfma_f32_32x32x16_bf16 v[98:113], v[180:183], v[134:137], v[98:113]
	ds_read_b128 v[172:175], v164 offset:8704
	v_exp_f32_e32 v72, v72
	v_exp_f32_e32 v73, v73
	v_cvt_pk_bf16_f32 v34, v66, v67
	v_cvt_pk_bf16_f32 v35, v68, v69
	s_waitcnt lgkmcnt(4)
	v_mfma_f32_32x32x16_bf16 v[114:129], v[184:187], v[134:137], v[114:129]
	ds_read_b128 v[176:179], v164 offset:10240
	v_exp_f32_e32 v74, v74
	v_exp_f32_e32 v75, v75
	v_cvt_pk_bf16_f32 v36, v70, v71
	v_cvt_pk_bf16_f32 v37, v72, v73
	v_mfma_f32_32x32x16_bf16 v[98:113], v[188:191], v[138:141], v[98:113]
	ds_read_b128 v[180:183], v164 offset:10752
	v_exp_f32_e32 v76, v76
	v_exp_f32_e32 v77, v77
	v_exp_f32_e32 v78, v78
	v_mfma_f32_32x32x16_bf16 v[114:129], v[192:195], v[138:141], v[114:129]
	ds_read_b128 v[184:187], v165 offset:12288
	v_exp_f32_e32 v79, v79
	v_exp_f32_e32 v80, v80
	v_exp_f32_e32 v81, v81
	s_waitcnt lgkmcnt(4)
	v_mfma_f32_32x32x16_bf16 v[98:113], v[240:243], v[142:145], v[98:113]
	ds_read_b128 v[188:191], v165 offset:12800
	v_exp_f32_e32 v50, v50
	v_exp_f32_e32 v51, v51
	v_cvt_pk_bf16_f32 v38, v74, v75
	v_cvt_pk_bf16_f32 v39, v76, v77
	v_mfma_f32_32x32x16_bf16 v[114:129], v[244:247], v[142:145], v[114:129]
	ds_read_b128 v[192:195], v165 offset:14336
	v_exp_f32_e32 v52, v52
	v_exp_f32_e32 v53, v53
	v_cvt_pk_bf16_f32 v40, v78, v79
	v_cvt_pk_bf16_f32 v41, v80, v81
	v_mfma_f32_32x32x16_bf16 v[98:113], v[248:251], v[146:149], v[98:113]
	ds_read_b128 v[240:243], v165 offset:14848
	v_exp_f32_e32 v54, v54
	v_exp_f32_e32 v55, v55
	v_exp_f32_e32 v56, v56
	s_waitcnt lgkmcnt(4)
	v_mfma_f32_32x32x16_bf16 v[114:129], v[172:175], v[146:149], v[114:129]
	ds_read_b128 v[244:247], v165 offset:16384
	v_exp_f32_e32 v57, v57
	v_exp_f32_e32 v58, v58
	v_cvt_pk_bf16_f32 v42, v50, v51
	v_cvt_pk_bf16_f32 v43, v52, v53
	v_mfma_f32_32x32x16_bf16 v[98:113], v[176:179], v[130:133], v[98:113]
	ds_read_b128 v[248:251], v165 offset:16896
	v_exp_f32_e32 v59, v59
	v_exp_f32_e32 v60, v60
	v_cvt_pk_bf16_f32 v44, v54, v55
	v_cvt_pk_bf16_f32 v45, v56, v57
	v_mfma_f32_32x32x16_bf16 v[114:129], v[180:183], v[130:133], v[114:129]
	ds_read_b128 v[172:175], v165 offset:18432
	v_exp_f32_e32 v61, v61
	v_exp_f32_e32 v62, v62
	v_exp_f32_e32 v63, v63
	s_waitcnt lgkmcnt(4)
	v_mfma_f32_32x32x16_bf16 v[2:17], v[184:187], v[34:37], v[2:17]
	ds_read_b128 v[176:179], v165 offset:18944
	v_exp_f32_e32 v64, v64
	v_exp_f32_e32 v65, v65
	v_cvt_pk_bf16_f32 v46, v58, v59
	v_cvt_pk_bf16_f32 v47, v60, v61
	v_mfma_f32_32x32x16_bf16 v[18:33], v[188:191], v[34:37], v[18:33]
	v_cvt_pk_bf16_f32 v48, v62, v63
	v_cvt_pk_bf16_f32 v49, v64, v65
	v_add_f32_e32 v166, v66, v67
	v_add_f32_e32 v167, v68, v69
	v_add_f32_e32 v168, v70, v71
	v_add_f32_e32 v169, v72, v73
	v_mfma_f32_32x32x16_bf16 v[2:17], v[192:195], v[38:41], v[2:17]
	v_add_f32_e32 v166, v166, v74
	v_add_f32_e32 v167, v167, v75
	v_add_f32_e32 v168, v168, v76
	v_add_f32_e32 v169, v169, v77
	v_max3_f32 v162, v98, v99, v100
	v_max3_f32 v163, v114, v115, v116
	s_waitcnt lgkmcnt(2)
	v_mfma_f32_32x32x16_bf16 v[18:33], v[240:243], v[38:41], v[18:33]
	v_add_f32_e32 v166, v166, v78
	v_add_f32_e32 v167, v167, v79
	v_add_f32_e32 v168, v168, v80
	v_add_f32_e32 v169, v169, v81
	v_max3_f32 v162, v162, v101, v102
	v_max3_f32 v163, v163, v117, v118
	v_mfma_f32_32x32x16_bf16 v[2:17], v[244:247], v[42:45], v[2:17]
	v_add_f32_e32 v166, v166, v50
	v_add_f32_e32 v167, v167, v51
	v_add_f32_e32 v168, v168, v52
	v_add_f32_e32 v169, v169, v53
	v_max3_f32 v162, v162, v103, v104
	v_max3_f32 v163, v163, v119, v120
	v_mfma_f32_32x32x16_bf16 v[18:33], v[248:251], v[42:45], v[18:33]
	v_add_f32_e32 v166, v166, v54
	v_add_f32_e32 v167, v167, v55
	v_add_f32_e32 v168, v168, v56
	v_add_f32_e32 v169, v169, v57
	v_max3_f32 v162, v162, v105, v106
	v_max3_f32 v163, v163, v121, v122
	s_waitcnt lgkmcnt(0)
	v_mfma_f32_32x32x16_bf16 v[2:17], v[172:175], v[46:49], v[2:17]
	v_add_f32_e32 v166, v166, v58
	v_add_f32_e32 v167, v167, v59
	v_add_f32_e32 v168, v168, v60
	v_add_f32_e32 v169, v169, v61
	v_max3_f32 v162, v162, v107, v108
	v_max3_f32 v163, v163, v123, v124
	v_mfma_f32_32x32x16_bf16 v[18:33], v[176:179], v[46:49], v[18:33]
	v_add_f32_e32 v166, v166, v62
	v_add_f32_e32 v167, v167, v63
	v_add_f32_e32 v168, v168, v64
	v_add_f32_e32 v169, v169, v65
	v_max3_f32 v162, v162, v109, v110
	v_max3_f32 v163, v163, v125, v126
	v_max3_f32 v162, v162, v111, v112
	v_max3_f32 v163, v163, v127, v128
	v_add_f32_e32 v166, v166, v167
	v_add_f32_e32 v168, v168, v169
	v_add_f32_e32 v166, v166, v168
	v_add_f32_e32 v170, v170, v166
	v_max3_f32 v162, v162, v113, v129
	v_max_f32_e32 v162, v162, v163
	s_waitcnt vmcnt(2)
	s_barrier
	v_add_u32_e32 v164, s18, v238
	v_add_u32_e32 v165, s15, v238
	ds_read_b128 v[172:175], v164
	ds_read_b128 v[176:179], v164 offset:512
	ds_read_b128 v[180:183], v164 offset:2048
	ds_read_b128 v[184:187], v164 offset:2560
	ds_read_b128 v[188:191], v164 offset:4096
	ds_read_b128 v[192:195], v164 offset:4608
	ds_read_b128 v[240:243], v164 offset:6144
	s_add_i32 s24, s14, s4
	s_mov_b32 m0, s24
	s_andn2_b64 vcc, exec, s[16:17]
	global_load_lds_dwordx4 v154, s[34:35]
	s_add_i32 m0, s24, 0x3000
	v_add_u32_e32 v154, 0x10000, v154
	global_load_lds_dwordx4 v156, s[28:29]
	v_add_u32_e32 v156, 0x80, v156
	s_cbranch_vccnz .LmlaLB_nokr
	s_add_i32 m0, s24, 0x2000
	s_nop 0
	global_load_lds_dwordx4 v158, s[38:39]
	v_add_u32_e32 v158, 0x10000, v158

; template <bool SWA> ...
;     ...
;     int t = 0;
;     if (wv >= 4) __builtin_amdgcn_s_setprio(1);
;     for (; t < ntiles - 2; t += 2) { AT_STEP(t, sA0, sA1, sB0, sB1, true); AT_STEP(t + 1, sB0, sB1, sA0, sA1, true); }
.LmlaLB_common:
	s_waitcnt lgkmcnt(4)
	v_mfma_f32_32x32x16_bf16 v[66:81], v[172:175], v[150:153], v[82:97]
	ds_read_b128 v[244:247], v164 offset:6656
	v_exp_f32_e32 v98, v98
	v_exp_f32_e32 v99, v99
	v_exp_f32_e32 v100, v100
	v_mfma_f32_32x32x16_bf16 v[50:65], v[176:179], v[150:153], v[82:97]
	ds_read_b128 v[248:251], v164 offset:8192
	v_exp_f32_e32 v101, v101
	v_exp_f32_e32 v102, v102
	v_exp_f32_e32 v103, v103
	v_mfma_f32_32x32x16_bf16 v[66:81], v[180:183], v[134:137], v[66:81]
	ds_read_b128 v[172:175], v164 offset:8704
	v_exp_f32_e32 v104, v104
	v_exp_f32_e32 v105, v105
	v_cvt_pk_bf16_f32 v34, v98, v99
	v_cvt_pk_bf16_f32 v35, v100, v101
	s_waitcnt lgkmcnt(4)
	v_mfma_f32_32x32x16_bf16 v[50:65], v[184:187], v[134:137], v[50:65]
	ds_read_b128 v[176:179], v164 offset:10240
	v_exp_f32_e32 v106, v106
	v_exp_f32_e32 v107, v107
	v_cvt_pk_bf16_f32 v36, v102, v103
	v_cvt_pk_bf16_f32 v37, v104, v105
	v_mfma_f32_32x32x16_bf16 v[66:81], v[188:191], v[138:141], v[66:81]
	ds_read_b128 v[180:183], v164 offset:10752
	v_exp_f32_e32 v108, v108
	v_exp_f32_e32 v109, v109
	v_exp_f32_e32 v110, v110
	v_mfma_f32_32x32x16_bf16 v[50:65], v[192:195], v[138:141], v[50:65]
	ds_read_b128 v[184:187], v165 offset:12288
	v_exp_f32_e32 v111, v111
	v_exp_f32_e32 v112, v112
	v_exp_f32_e32 v113, v113
	s_waitcnt lgkmcnt(4)
	v_mfma_f32_32x32x16_bf16 v[66:81], v[240:243], v[142:145], v[66:81]
	ds_read_b128 v[188:191], v165 offset:12800
	v_exp_f32_e32 v114, v114
	v_exp_f32_e32 v115, v115
	v_cvt_pk_bf16_f32 v38, v106, v107
	v_cvt_pk_bf16_f32 v39, v108, v109
	v_mfma_f32_32x32x16_bf16 v[50:65], v[244:247], v[142:145], v[50:65]
	ds_read_b128 v[192:195], v165 offset:14336
	v_exp_f32_e32 v116, v116
	v_exp_f32_e32 v117, v117
	v_cvt_pk_bf16_f32 v40, v110, v111
	v_cvt_pk_bf16_f32 v41, v112, v113
	v_mfma_f32_32x32x16_bf16 v[66:81], v[248:251], v[146:149], v[66:81]
	ds_read_b128 v[240:243], v165 offset:14848
	v_exp_f32_e32 v118, v118
	v_exp_f32_e32 v119, v119
	v_exp_f32_e32 v120, v120
	s_waitcnt lgkmcnt(4)
	v_mfma_f32_32x32x16_bf16 v[50:65], v[172:175], v[146:149], v[50:65]
	ds_read_b128 v[244:247], v165 offset:16384
	v_exp_f32_e32 v121, v121
	v_exp_f32_e32 v122, v122
	v_cvt_pk_bf16_f32 v42, v114, v115
	v_cvt_pk_bf16_f32 v43, v116, v117
	v_mfma_f32_32x32x16_bf16 v[66:81], v[176:179], v[130:133], v[66:81]
	ds_read_b128 v[248:251], v165 offset:16896
	v_exp_f32_e32 v123, v123
	v_exp_f32_e32 v124, v124
	v_cvt_pk_bf16_f32 v44, v118, v119
	v_cvt_pk_bf16_f32 v45, v120, v121
	v_mfma_f32_32x32x16_bf16 v[50:65], v[180:183], v[130:133], v[50:65]
	ds_read_b128 v[172:175], v165 offset:18432
	v_exp_f32_e32 v125, v125
	v_exp_f32_e32 v126, v126
	v_exp_f32_e32 v127, v127
	s_waitcnt lgkmcnt(4)
	v_mfma_f32_32x32x16_bf16 v[2:17], v[184:187], v[34:37], v[2:17]
	ds_read_b128 v[176:179], v165 offset:18944
	v_exp_f32_e32 v128, v128
	v_exp_f32_e32 v129, v129
	v_cvt_pk_bf16_f32 v46, v122, v123
	v_cvt_pk_bf16_f32 v47, v124, v125
	v_mfma_f32_32x32x16_bf16 v[18:33], v[188:191], v[34:37], v[18:33]
	v_cvt_pk_bf16_f32 v48, v126, v127
	v_cvt_pk_bf16_f32 v49, v128, v129
	v_add_f32_e32 v166, v98, v99
	v_add_f32_e32 v167, v100, v101
	v_add_f32_e32 v168, v102, v103
	v_add_f32_e32 v169, v104, v105
	v_mfma_f32_32x32x16_bf16 v[2:17], v[192:195], v[38:41], v[2:17]
	v_add_f32_e32 v166, v166, v106
	v_add_f32_e32 v167, v167, v107
	v_add_f32_e32 v168, v168, v108
	v_add_f32_e32 v169, v169, v109
	v_max3_f32 v162, v66, v67, v68
	v_max3_f32 v163, v50, v51, v52
	s_waitcnt lgkmcnt(2)
	v_mfma_f32_32x32x16_bf16 v[18:33], v[240:243], v[38:41], v[18:33]
	v_add_f32_e32 v166, v166, v110
	v_add_f32_e32 v167, v167, v111
	v_add_f32_e32 v168, v168, v112
	v_add_f32_e32 v169, v169, v113
	v_max3_f32 v162, v162, v69, v70
	v_max3_f32 v163, v163, v53, v54
	v_mfma_f32_32x32x16_bf16 v[2:17], v[244:247], v[42:45], v[2:17]
	v_add_f32_e32 v166, v166, v114
	v_add_f32_e32 v167, v167, v115
	v_add_f32_e32 v168, v168, v116
	v_add_f32_e32 v169, v169, v117
	v_max3_f32 v162, v162, v71, v72
	v_max3_f32 v163, v163, v55, v56
	v_mfma_f32_32x32x16_bf16 v[18:33], v[248:251], v[42:45], v[18:33]
	v_add_f32_e32 v166, v166, v118
	v_add_f32_e32 v167, v167, v119
	v_add_f32_e32 v168, v168, v120
	v_add_f32_e32 v169, v169, v121
	v_max3_f32 v162, v162, v73, v74
	v_max3_f32 v163, v163, v57, v58
	s_waitcnt lgkmcnt(0)
	v_mfma_f32_32x32x16_bf16 v[2:17], v[172:175], v[46:49], v[2:17]
	v_add_f32_e32 v166, v166, v122
	v_add_f32_e32 v167, v167, v123
	v_add_f32_e32 v168, v168, v124
	v_add_f32_e32 v169, v169, v125
	v_max3_f32 v162, v162, v75, v76
	v_max3_f32 v163, v163, v59, v60
	v_mfma_f32_32x32x16_bf16 v[18:33], v[176:179], v[46:49], v[18:33]
	v_add_f32_e32 v166, v166, v126
	v_add_f32_e32 v167, v167, v127
	v_add_f32_e32 v168, v168, v128
	v_add_f32_e32 v169, v169, v129
	v_max3_f32 v162, v162, v77, v78
	v_max3_f32 v163, v163, v61, v62
	v_max3_f32 v162, v162, v79, v80
	v_max3_f32 v163, v163, v63, v64
	v_add_f32_e32 v166, v166, v167
	v_add_f32_e32 v168, v168, v169
	v_add_f32_e32 v166, v166, v168
	v_add_f32_e32 v170, v170, v166
	v_max3_f32 v162, v162, v81, v65
	v_max_f32_e32 v162, v162, v163
	s_add_i32 s19, s19, 2
	s_waitcnt vmcnt(2)
	s_barrier
	s_cmpk_lt_u32 s19, 0x7c
	s_cbranch_scc0 .LmlaL_exit
	s_mov_b32 s5, s4
	s_mov_b32 s4, s18
	s_mov_b32 s18, s5
	s_mov_b32 s5, s15
	s_mov_b32 s15, s20
	s_mov_b32 s20, s5
	s_branch .LmlaL_top

; template <bool SWA> ...
;     ...
;     const int koff = pkey * ldk + 8 * wv, voff = lane * T + 8 * wv, roff = pkey * 512 + 8 * (wv & 3);
;     const bool do_r = (!SWA) && wv < 4;
;     const int kfo = hi * 1024 + l32 * 16, vfo = AT_KB + hi * 1024 + l32 * 16;
;     ...
;     AT_GLOAD(0, 0); AT_GLOAD(1, AT_BUF);
;     asm volatile("s_waitcnt vmcnt(0)" ::: "memory");
;     __syncthreads();
;     f32x16 o0, o1, negm;
;     float mref = SWA ? m_init : 0.f, lrun = l_init;
; #pragma unroll
;     for (int r = 0; r < 16; ++r) { o0[r] = 0.f; o1[r] = 0.f; negm[r] = -mref; }
.LBB0_1034:
	s_lshr_b32 s14, s13, 4
	s_and_b32 s14, s14, 7
	s_lshl_b32 s20, s14, 7
	v_add_u32_e32 v6, s19, v236
	s_lshl_b32 s12, s12, 6
	s_lshl_b32 s14, s14, 22
	v_lshl_or_b32 v206, v6, 1, s4
	s_or_b32 s4, s4, s20
	v_mov_b32_e32 v6, s4
	s_add_u32 s4, s14, s6
	v_mov_b32_e32 v207, s5
	v_mov_b32_e32 v7, s5
	s_addc_u32 s5, 0, s7
	v_mov_b32_e32 v16, v1
	v_mov_b32_e32 v17, v1
	v_lshl_add_u64 v[208:209], v[4:5], 1, v[6:7]
	v_lshl_add_u64 v[210:211], v[2:3], 1, s[4:5]
	v_mov_b32_e32 v2, v1
	v_mov_b32_e32 v3, v1
	v_mov_b32_e32 v4, v1
	v_mov_b32_e32 v5, v1
	v_mov_b32_e32 v6, v1
	v_mov_b32_e32 v7, v1
	v_mov_b32_e32 v8, v1
	v_mov_b32_e32 v9, v1
	v_mov_b32_e32 v10, v1
	v_mov_b32_e32 v11, v1
	v_mov_b32_e32 v12, v1
	v_mov_b32_e32 v13, v1
	v_mov_b32_e32 v14, v1
	v_mov_b32_e32 v15, v1
	v_bfrev_b32_e32 v82, 1
	v_mov_b64_e32 v[32:33], v[16:17]
	v_readlane_b32 s24, v254, 54
	s_mov_b32 s4, 0
	s_mov_b32 s20, 0xa000
	s_movk_i32 s19, 0x5000
	v_mov_b32_e32 v239, 0
	s_mov_b32 s21, -2
	v_mov_b64_e32 v[30:31], v[14:15]
	v_mov_b64_e32 v[28:29], v[12:13]
	v_mov_b64_e32 v[26:27], v[10:11]
	v_mov_b64_e32 v[24:25], v[8:9]
	v_mov_b64_e32 v[22:23], v[6:7]
	v_mov_b64_e32 v[20:21], v[4:5]
	v_mov_b64_e32 v[18:19], v[2:3]
	v_mov_b32_e32 v160, 0
	v_mov_b32_e32 v83, v82
	v_mov_b32_e32 v84, v82
	v_mov_b32_e32 v85, v82
	v_mov_b32_e32 v86, v82
	v_mov_b32_e32 v87, v82
	v_mov_b32_e32 v88, v82
	v_mov_b32_e32 v89, v82
	v_mov_b32_e32 v90, v82
	v_mov_b32_e32 v91, v82
	v_mov_b32_e32 v92, v82
	v_mov_b32_e32 v93, v82
	v_mov_b32_e32 v94, v82
	v_mov_b32_e32 v95, v82
	v_mov_b32_e32 v96, v82
	v_mov_b32_e32 v97, v82
	v_readlane_b32 s26, v254, 56
	v_readlane_b32 s27, v254, 57
	v_readlane_b32 s25, v254, 55
	s_mov_b32 s23, 0xf000
	v_readfirstlane_b32 s6, v208
	v_readfirstlane_b32 s7, v209
	v_readfirstlane_b32 s24, v210
	v_readfirstlane_b32 s25, v211
	s_add_u32 s34, s26, s6
	s_addc_u32 s35, s27, s7
	s_add_u32 s34, s34, 0x16020000
	s_addc_u32 s35, s35, 0
	v_subrev_u32_e32 v154, s6, v208
	s_add_u32 s28, s26, s24
	s_addc_u32 s29, s27, s25
	s_add_u32 s28, s28, 0x18000100
	s_addc_u32 s29, s29, 0
	v_subrev_u32_e32 v156, s24, v210
	v_readfirstlane_b32 s6, v206
	v_readfirstlane_b32 s7, v207
	s_nop 1
	s_add_u32 s38, s26, s6
	s_addc_u32 s39, s27, s7
	s_add_u32 s38, s38, 0x7820300
	s_addc_u32 s39, s39, 0
	v_subrev_u32_e32 v158, s6, v206
	s_add_i32 s24, s15, s20
	s_mov_b32 m0, s24
	s_andn2_b64 vcc, exec, s[16:17]
	global_load_lds_dwordx4 v154, s[34:35]
	s_add_i32 m0, s24, 0x3000
	v_add_u32_e32 v154, 0x10000, v154
	global_load_lds_dwordx4 v156, s[28:29]
	v_add_u32_e32 v156, 0x80, v156
	s_cbranch_vccnz .LmlaSP_nokr
	s_add_i32 m0, s24, 0x2000
	s_nop 0
	global_load_lds_dwordx4 v158, s[38:39]
	v_add_u32_e32 v158, 0x10000, v158

.LmlaS_top:
	v_add_u32_e32 v164, s19, v238
	v_add_u32_e32 v165, s4, v238
	ds_read_b128 v[172:175], v164
	ds_read_b128 v[176:179], v164 offset:512
	ds_read_b128 v[180:183], v164 offset:2048
	ds_read_b128 v[184:187], v164 offset:2560
	ds_read_b128 v[188:191], v164 offset:4096
	ds_read_b128 v[192:195], v164 offset:4608
	ds_read_b128 v[240:243], v164 offset:6144
	s_add_i32 s24, s15, s23
	s_mov_b32 m0, s24
	s_andn2_b64 vcc, exec, s[16:17]
	global_load_lds_dwordx4 v154, s[34:35]
	s_add_i32 m0, s24, 0x3000
	v_add_u32_e32 v154, 0x10000, v154
	global_load_lds_dwordx4 v156, s[28:29]
	v_add_u32_e32 v156, 0x80, v156
	s_cbranch_vccnz .LmlaSA_nokr
	s_add_i32 m0, s24, 0x2000
	s_nop 0
	global_load_lds_dwordx4 v158, s[38:39]
	v_add_u32_e32 v158, 0x10000, v158

.LmlaSA_common:
	s_waitcnt lgkmcnt(4)
	v_mfma_f32_32x32x16_bf16 v[98:113], v[172:175], v[150:153], v[82:97]
	ds_read_b128 v[244:247], v164 offset:6656
	v_exp_f32_e32 v66, v66
	v_exp_f32_e32 v67, v67
	v_exp_f32_e32 v68, v68
	v_mfma_f32_32x32x16_bf16 v[114:129], v[176:179], v[150:153], v[82:97]
	ds_read_b128 v[248:251], v164 offset:8192
	v_exp_f32_e32 v69, v69
	v_exp_f32_e32 v70, v70
	v_exp_f32_e32 v71, v71
	v_mfma_f32_32x32x16_bf16 v[98:113], v[180:183], v[146:149], v[98:113]
	ds_read_b128 v[172:175], v164 offset:8704
	v_exp_f32_e32 v72, v72
	v_exp_f32_e32 v73, v73
	v_cvt_pk_bf16_f32 v34, v66, v67
	v_cvt_pk_bf16_f32 v35, v68, v69
	s_waitcnt lgkmcnt(4)
	v_mfma_f32_32x32x16_bf16 v[114:129], v[184:187], v[146:149], v[114:129]
	ds_read_b128 v[176:179], v164 offset:10240
	v_exp_f32_e32 v74, v74
	v_exp_f32_e32 v75, v75
	v_cvt_pk_bf16_f32 v36, v70, v71
	v_cvt_pk_bf16_f32 v37, v72, v73
	v_mfma_f32_32x32x16_bf16 v[98:113], v[188:191], v[142:145], v[98:113]
	ds_read_b128 v[180:183], v164 offset:10752
	v_exp_f32_e32 v76, v76
	v_exp_f32_e32 v77, v77
	v_exp_f32_e32 v78, v78
	v_mfma_f32_32x32x16_bf16 v[114:129], v[192:195], v[142:145], v[114:129]
	ds_read_b128 v[184:187], v165 offset:12288
	v_exp_f32_e32 v79, v79
	v_exp_f32_e32 v80, v80
	v_exp_f32_e32 v81, v81
	s_waitcnt lgkmcnt(4)
	v_mfma_f32_32x32x16_bf16 v[98:113], v[240:243], v[138:141], v[98:113]
	ds_read_b128 v[188:191], v165 offset:12800
	v_exp_f32_e32 v50, v50
	v_exp_f32_e32 v51, v51
	v_cvt_pk_bf16_f32 v38, v74, v75
	v_cvt_pk_bf16_f32 v39, v76, v77
	v_mfma_f32_32x32x16_bf16 v[114:129], v[244:247], v[138:141], v[114:129]
	ds_read_b128 v[192:195], v165 offset:14336
	v_exp_f32_e32 v52, v52
	v_exp_f32_e32 v53, v53
	v_cvt_pk_bf16_f32 v40, v78, v79
	v_cvt_pk_bf16_f32 v41, v80, v81
	v_mfma_f32_32x32x16_bf16 v[98:113], v[248:251], v[134:137], v[98:113]
	ds_read_b128 v[240:243], v165 offset:14848
	v_exp_f32_e32 v54, v54
	v_exp_f32_e32 v55, v55
	v_exp_f32_e32 v56, v56
	s_waitcnt lgkmcnt(4)
	v_mfma_f32_32x32x16_bf16 v[114:129], v[172:175], v[134:137], v[114:129]
	ds_read_b128 v[244:247], v165 offset:16384
	v_exp_f32_e32 v57, v57
	v_exp_f32_e32 v58, v58
	v_cvt_pk_bf16_f32 v42, v50, v51
	v_cvt_pk_bf16_f32 v43, v52, v53
	v_mfma_f32_32x32x16_bf16 v[98:113], v[176:179], v[130:133], v[98:113]
	ds_read_b128 v[248:251], v165 offset:16896
	v_exp_f32_e32 v59, v59
	v_exp_f32_e32 v60, v60
	v_cvt_pk_bf16_f32 v44, v54, v55
	v_cvt_pk_bf16_f32 v45, v56, v57
	v_mfma_f32_32x32x16_bf16 v[114:129], v[180:183], v[130:133], v[114:129]
	ds_read_b128 v[172:175], v165 offset:18432
	v_exp_f32_e32 v61, v61
	v_exp_f32_e32 v62, v62
	v_exp_f32_e32 v63, v63
	s_waitcnt lgkmcnt(4)
	v_mfma_f32_32x32x16_bf16 v[2:17], v[184:187], v[34:37], v[2:17]
	ds_read_b128 v[176:179], v165 offset:18944
	v_exp_f32_e32 v64, v64
	v_exp_f32_e32 v65, v65
	v_cvt_pk_bf16_f32 v46, v58, v59
	v_cvt_pk_bf16_f32 v47, v60, v61
	v_mfma_f32_32x32x16_bf16 v[18:33], v[188:191], v[34:37], v[18:33]
	v_cvt_pk_bf16_f32 v48, v62, v63
	v_cvt_pk_bf16_f32 v49, v64, v65
	v_add_f32_e32 v166, v66, v67
	v_add_f32_e32 v167, v68, v69
	v_add_f32_e32 v168, v70, v71
	v_add_f32_e32 v169, v72, v73
	v_mfma_f32_32x32x16_bf16 v[2:17], v[192:195], v[38:41], v[2:17]
	v_add_f32_e32 v166, v166, v74
	v_add_f32_e32 v167, v167, v75
	v_add_f32_e32 v168, v168, v76
	v_add_f32_e32 v169, v169, v77
	v_max3_f32 v162, v98, v99, v100
	v_max3_f32 v163, v114, v115, v116
	s_waitcnt lgkmcnt(2)
	v_mfma_f32_32x32x16_bf16 v[18:33], v[240:243], v[38:41], v[18:33]
	v_add_f32_e32 v166, v166, v78
	v_add_f32_e32 v167, v167, v79
	v_add_f32_e32 v168, v168, v80
	v_add_f32_e32 v169, v169, v81
	v_max3_f32 v162, v162, v101, v102
	v_max3_f32 v163, v163, v117, v118
	v_mfma_f32_32x32x16_bf16 v[2:17], v[244:247], v[42:45], v[2:17]
	v_add_f32_e32 v166, v166, v50
	v_add_f32_e32 v167, v167, v51
	v_add_f32_e32 v168, v168, v52
	v_add_f32_e32 v169, v169, v53
	v_max3_f32 v162, v162, v103, v104
	v_max3_f32 v163, v163, v119, v120
	v_mfma_f32_32x32x16_bf16 v[18:33], v[248:251], v[42:45], v[18:33]
	v_add_f32_e32 v166, v166, v54
	v_add_f32_e32 v167, v167, v55
	v_add_f32_e32 v168, v168, v56
	v_add_f32_e32 v169, v169, v57
	v_max3_f32 v162, v162, v105, v106
	v_max3_f32 v163, v163, v121, v122
	s_waitcnt lgkmcnt(0)
	v_mfma_f32_32x32x16_bf16 v[2:17], v[172:175], v[46:49], v[2:17]
	v_add_f32_e32 v166, v166, v58
	v_add_f32_e32 v167, v167, v59
	v_add_f32_e32 v168, v168, v60
	v_add_f32_e32 v169, v169, v61
	v_max3_f32 v162, v162, v107, v108
	v_max3_f32 v163, v163, v123, v124
	v_mfma_f32_32x32x16_bf16 v[18:33], v[176:179], v[46:49], v[18:33]
	v_add_f32_e32 v166, v166, v62
	v_add_f32_e32 v167, v167, v63
	v_add_f32_e32 v168, v168, v64
	v_add_f32_e32 v169, v169, v65
	v_max3_f32 v162, v162, v109, v110
	v_max3_f32 v163, v163, v125, v126
	v_max3_f32 v162, v162, v111, v112
	v_max3_f32 v163, v163, v127, v128
	v_add_f32_e32 v166, v166, v167
	v_add_f32_e32 v168, v168, v169
	v_add_f32_e32 v166, v166, v168
	v_add_f32_e32 v160, v160, v166
	v_max3_f32 v162, v162, v113, v129
	v_max_f32_e32 v162, v162, v163
	s_waitcnt vmcnt(2)
	s_barrier
	v_add_u32_e32 v164, s20, v238
	v_add_u32_e32 v165, s19, v238
	ds_read_b128 v[172:175], v164
	ds_read_b128 v[176:179], v164 offset:512
	ds_read_b128 v[180:183], v164 offset:2048
	ds_read_b128 v[184:187], v164 offset:2560
	ds_read_b128 v[188:191], v164 offset:4096
	ds_read_b128 v[192:195], v164 offset:4608
	ds_read_b128 v[240:243], v164 offset:6144
	s_add_i32 s24, s18, s4
	s_mov_b32 m0, s24
	s_andn2_b64 vcc, exec, s[16:17]
	global_load_lds_dwordx4 v154, s[34:35]
	s_add_i32 m0, s24, 0x3000
	v_add_u32_e32 v154, 0x10000, v154
	global_load_lds_dwordx4 v156, s[28:29]
	v_add_u32_e32 v156, 0x80, v156
	s_cbranch_vccnz .LmlaSB_nokr
	s_add_i32 m0, s24, 0x2000
	s_nop 0
	global_load_lds_dwordx4 v158, s[38:39]
	v_add_u32_e32 v158, 0x10000, v158

; template <bool SWA> ...
;     ...
;     int t = 0;
;     if (wv >= 4) __builtin_amdgcn_s_setprio(1);
;     for (; t < ntiles - 2; t += 2) { AT_STEP(t, sA0, sA1, sB0, sB1, true); AT_STEP(t + 1, sB0, sB1, sA0, sA1, true); }
.LmlaSB_common:
	s_waitcnt lgkmcnt(4)
	v_mfma_f32_32x32x16_bf16 v[66:81], v[172:175], v[150:153], v[82:97]
	ds_read_b128 v[244:247], v164 offset:6656
	v_exp_f32_e32 v98, v98
	v_exp_f32_e32 v99, v99
	v_exp_f32_e32 v100, v100
	v_mfma_f32_32x32x16_bf16 v[50:65], v[176:179], v[150:153], v[82:97]
	ds_read_b128 v[248:251], v164 offset:8192
	v_exp_f32_e32 v101, v101
	v_exp_f32_e32 v102, v102
	v_exp_f32_e32 v103, v103
	v_mfma_f32_32x32x16_bf16 v[66:81], v[180:183], v[146:149], v[66:81]
	ds_read_b128 v[172:175], v164 offset:8704
	v_exp_f32_e32 v104, v104
	v_exp_f32_e32 v105, v105
	v_cvt_pk_bf16_f32 v34, v98, v99
	v_cvt_pk_bf16_f32 v35, v100, v101
	s_waitcnt lgkmcnt(4)
	v_mfma_f32_32x32x16_bf16 v[50:65], v[184:187], v[146:149], v[50:65]
	ds_read_b128 v[176:179], v164 offset:10240
	v_exp_f32_e32 v106, v106
	v_exp_f32_e32 v107, v107
	v_cvt_pk_bf16_f32 v36, v102, v103
	v_cvt_pk_bf16_f32 v37, v104, v105
	v_mfma_f32_32x32x16_bf16 v[66:81], v[188:191], v[142:145], v[66:81]
	ds_read_b128 v[180:183], v164 offset:10752
	v_exp_f32_e32 v108, v108
	v_exp_f32_e32 v109, v109
	v_exp_f32_e32 v110, v110
	v_mfma_f32_32x32x16_bf16 v[50:65], v[192:195], v[142:145], v[50:65]
	ds_read_b128 v[184:187], v165 offset:12288
	v_exp_f32_e32 v111, v111
	v_exp_f32_e32 v112, v112
	v_exp_f32_e32 v113, v113
	s_waitcnt lgkmcnt(4)
	v_mfma_f32_32x32x16_bf16 v[66:81], v[240:243], v[138:141], v[66:81]
	ds_read_b128 v[188:191], v165 offset:12800
	v_exp_f32_e32 v114, v114
	v_exp_f32_e32 v115, v115
	v_cvt_pk_bf16_f32 v38, v106, v107
	v_cvt_pk_bf16_f32 v39, v108, v109
	v_mfma_f32_32x32x16_bf16 v[50:65], v[244:247], v[138:141], v[50:65]
	ds_read_b128 v[192:195], v165 offset:14336
	v_exp_f32_e32 v116, v116
	v_exp_f32_e32 v117, v117
	v_cvt_pk_bf16_f32 v40, v110, v111
	v_cvt_pk_bf16_f32 v41, v112, v113
	v_mfma_f32_32x32x16_bf16 v[66:81], v[248:251], v[134:137], v[66:81]
	ds_read_b128 v[240:243], v165 offset:14848
	v_exp_f32_e32 v118, v118
	v_exp_f32_e32 v119, v119
	v_exp_f32_e32 v120, v120
	s_waitcnt lgkmcnt(4)
	v_mfma_f32_32x32x16_bf16 v[50:65], v[172:175], v[134:137], v[50:65]
	ds_read_b128 v[244:247], v165 offset:16384
	v_exp_f32_e32 v121, v121
	v_exp_f32_e32 v122, v122
	v_cvt_pk_bf16_f32 v42, v114, v115
	v_cvt_pk_bf16_f32 v43, v116, v117
	v_mfma_f32_32x32x16_bf16 v[66:81], v[176:179], v[130:133], v[66:81]
	ds_read_b128 v[248:251], v165 offset:16896
	v_exp_f32_e32 v123, v123
	v_exp_f32_e32 v124, v124
	v_cvt_pk_bf16_f32 v44, v118, v119
	v_cvt_pk_bf16_f32 v45, v120, v121
	v_mfma_f32_32x32x16_bf16 v[50:65], v[180:183], v[130:133], v[50:65]
	ds_read_b128 v[172:175], v165 offset:18432
	v_exp_f32_e32 v125, v125
	v_exp_f32_e32 v126, v126
	v_exp_f32_e32 v127, v127
	s_waitcnt lgkmcnt(4)
	v_mfma_f32_32x32x16_bf16 v[2:17], v[184:187], v[34:37], v[2:17]
	ds_read_b128 v[176:179], v165 offset:18944
	v_exp_f32_e32 v128, v128
	v_exp_f32_e32 v129, v129
	v_cvt_pk_bf16_f32 v46, v122, v123
	v_cvt_pk_bf16_f32 v47, v124, v125
	v_mfma_f32_32x32x16_bf16 v[18:33], v[188:191], v[34:37], v[18:33]
	v_cvt_pk_bf16_f32 v48, v126, v127
	v_cvt_pk_bf16_f32 v49, v128, v129
	v_add_f32_e32 v166, v98, v99
	v_add_f32_e32 v167, v100, v101
	v_add_f32_e32 v168, v102, v103
	v_add_f32_e32 v169, v104, v105
	v_mfma_f32_32x32x16_bf16 v[2:17], v[192:195], v[38:41], v[2:17]
	v_add_f32_e32 v166, v166, v106
	v_add_f32_e32 v167, v167, v107
	v_add_f32_e32 v168, v168, v108
	v_add_f32_e32 v169, v169, v109
	v_max3_f32 v162, v66, v67, v68
	v_max3_f32 v163, v50, v51, v52
	s_waitcnt lgkmcnt(2)
	v_mfma_f32_32x32x16_bf16 v[18:33], v[240:243], v[38:41], v[18:33]
	v_add_f32_e32 v166, v166, v110
	v_add_f32_e32 v167, v167, v111
	v_add_f32_e32 v168, v168, v112
	v_add_f32_e32 v169, v169, v113
	v_max3_f32 v162, v162, v69, v70
	v_max3_f32 v163, v163, v53, v54
	v_mfma_f32_32x32x16_bf16 v[2:17], v[244:247], v[42:45], v[2:17]
	v_add_f32_e32 v166, v166, v114
	v_add_f32_e32 v167, v167, v115
	v_add_f32_e32 v168, v168, v116
	v_add_f32_e32 v169, v169, v117
	v_max3_f32 v162, v162, v71, v72
	v_max3_f32 v163, v163, v55, v56
	v_mfma_f32_32x32x16_bf16 v[18:33], v[248:251], v[42:45], v[18:33]
	v_add_f32_e32 v166, v166, v118
	v_add_f32_e32 v167, v167, v119
	v_add_f32_e32 v168, v168, v120
	v_add_f32_e32 v169, v169, v121
	v_max3_f32 v162, v162, v73, v74
	v_max3_f32 v163, v163, v57, v58
	s_waitcnt lgkmcnt(0)
	v_mfma_f32_32x32x16_bf16 v[2:17], v[172:175], v[46:49], v[2:17]
	v_add_f32_e32 v166, v166, v122
	v_add_f32_e32 v167, v167, v123
	v_add_f32_e32 v168, v168, v124
	v_add_f32_e32 v169, v169, v125
	v_max3_f32 v162, v162, v75, v76
	v_max3_f32 v163, v163, v59, v60
	v_mfma_f32_32x32x16_bf16 v[18:33], v[176:179], v[46:49], v[18:33]
	v_add_f32_e32 v166, v166, v126
	v_add_f32_e32 v167, v167, v127
	v_add_f32_e32 v168, v168, v128
	v_add_f32_e32 v169, v169, v129
	v_max3_f32 v162, v162, v77, v78
	v_max3_f32 v163, v163, v61, v62
	v_max3_f32 v162, v162, v79, v80
	v_max3_f32 v163, v163, v63, v64
	v_add_f32_e32 v166, v166, v167
	v_add_f32_e32 v168, v168, v169
	v_add_f32_e32 v166, v166, v168
	v_add_f32_e32 v160, v160, v166
	v_max3_f32 v162, v162, v81, v65
	v_max_f32_e32 v162, v162, v163
	s_add_i32 s21, s21, 2
	s_waitcnt vmcnt(2)
	s_barrier
	s_cmp_lt_u32 s21, 60
	s_cbranch_scc0 .LmlaS_exit
	s_mov_b32 s5, s4
	s_mov_b32 s4, s20
	s_mov_b32 s20, s5
	s_mov_b32 s5, s19
	s_mov_b32 s19, s23
	s_mov_b32 s23, s5
	s_branch .LmlaS_top
